# G1B K-loop first iteration peeled as well (zero C operand), its accumulator zeroing moved off the hot path
# baseline (speedup 1.0000x reference)
; #define PG8_STAGE(bufoff, gbase, voff) do { _Pragma("unroll") for (int _i = 0; _i < 2; ++_i) \
;         __builtin_amdgcn_global_load_lds((const unsigned*)((const char*)(gbase) + (voff)[_i]), (PG8_LAS unsigned*)(lds + (bufoff) + ldsw + _i * 8192), 16, 0, 0); } while (0)
; #define PG8_LDA(dst, b, h) do { _Pragma("unroll") for (int m = 0; m < 4; ++m) _Pragma("unroll") for (int k = 0; k < 2; ++k) dst[m][k] = *(const PG8_LAS bf16x8*)(lds + PG8_SA(b, h) + aoff + m * 2048 + k * 1024); } while (0)
; #define PG8_LDB(dst, b, h) do { _Pragma("unroll") for (int n = 0; n < 2; ++n) _Pragma("unroll") for (int k = 0; k < 2; ++k) dst[n][k] = *(const PG8_LAS bf16x8*)(lds + PG8_SB(b, h) + boff + n * 2048 + k * 1024); } while (0)
; #define PG8_MMA(ai, bj, At, Bt) do { __builtin_amdgcn_s_setprio(1); _Pragma("unroll") for (int m = 0; m < 4; ++m) _Pragma("unroll") for (int n = 0; n < 2; ++n) _Pragma("unroll") for (int k = 0; k < 2; ++k) \
;         acc[ai][bj][m][n] = __builtin_amdgcn_mfma_f32_16x16x32_bf16(Bt[n][k], At[m][k], acc[ai][bj][m][n], 0, 0, 0); __builtin_amdgcn_s_setprio(0); } while (0)
; #define PG8_WAIT_V(n) asm volatile("s_waitcnt vmcnt(" #n ")" ::: "memory")
; #define PG8_WAIT_L(n) asm volatile("s_waitcnt lgkmcnt(" #n ")" ::: "memory")
; #define PG8_BAR __builtin_amdgcn_s_barrier()
; #define PG8_SCHED __builtin_amdgcn_sched_barrier(0)
; template <class Epi, class Sched, bool ALIGN_EPI = false, bool SP2 = false>
; __device__ __forceinline__ void gemm_phase(PG8_LAS unsigned char* lds, const Gemm g, const Sched& S, const Epi& E, const int wid) {
;     ...
;             PG8_LDB(B0, 0, 0); PG8_LDB(B1, 0, 1); PG8_SCHED; PG8_LDA(At, 0, 0); PG8_STAGE(PG8_SA(1, 1), a1 + hstep, voffA);
;             PG8_WAIT_V(8); PG8_WAIT_L(0); PG8_BAR; PG8_MMA(0, 0, At, B0); PG8_MMA(0, 1, At, B1); PG8_BAR; PG8_SCHED;
;             PG8_LDA(At, 0, 1); PG8_STAGE(PG8_SB(0, 0), b2, voffB); PG8_STAGE(PG8_SB(0, 1), b2 + hstep, voffB); PG8_STAGE(PG8_SA(0, 0), a2, voffA);
;             PG8_WAIT_V(8); PG8_WAIT_L(0); PG8_BAR; PG8_MMA(1, 0, At, B0); PG8_MMA(1, 1, At, B1); PG8_BAR; PG8_SCHED;
.LBB0_1098:
	s_andn2_b64 vcc, exec, s[28:29]
	s_cbranch_vccnz .Lz_G1B
	s_add_u32 s4, s8, 0x80
	s_addc_u32 s5, s9, 0
	s_add_u32 s0, s6, 0x100
	s_addc_u32 s1, s7, 0
	s_mov_b32 s6, 0
	ds_read_b128 v[44:47], v163
	ds_read_b128 v[52:55], v163 offset:1024
	ds_read_b128 v[60:63], v163 offset:2048
	ds_read_b128 v[68:71], v163 offset:3072
	ds_read_b128 v[166:169], v164
	ds_read_b128 v[170:173], v164 offset:1024
	ds_read_b128 v[174:177], v164 offset:2048
	ds_read_b128 v[178:181], v164 offset:3072
	s_add_i32 s8, s6, 2
	s_add_u32 s9, s4, 0x80
	s_addc_u32 s7, s5, 0
	s_cmp_eq_u32 s72, s6
	s_cselect_b32 s6, s48, s9
	s_cselect_b32 s7, s49, s7
	s_cselect_b32 s77, s51, s1
	s_cselect_b32 s76, s50, s0
	v_lshl_add_u64 v[158:159], s[4:5], 0, v[152:153]
	s_add_i32 m0, s63, 0xc000
	ds_read_b128 v[182:185], v165
	ds_read_b128 v[186:189], v165 offset:1024
	ds_read_b128 v[190:193], v165 offset:2048
	ds_read_b128 v[194:197], v165 offset:3072
	ds_read_b128 v[198:201], v165 offset:4096
	ds_read_b128 v[202:205], v165 offset:5120
	ds_read_b128 v[206:209], v165 offset:6144
	ds_read_b128 v[210:213], v165 offset:7168
	global_load_lds_dwordx4 v[158:159], off
	v_lshl_add_u64 v[158:159], s[4:5], 0, v[154:155]
	s_add_i32 m0, s63, 0xe000
	s_nop 0
	global_load_lds_dwordx4 v[158:159], off
	s_waitcnt vmcnt(8)
	s_waitcnt lgkmcnt(0)
	s_barrier
	s_setprio 1
	s_waitcnt lgkmcnt(0)
	v_mfma_f32_16x16x32_bf16 v[140:143], v[44:47], v[182:185], 0
	v_mfma_f32_16x16x32_bf16 v[136:139], v[60:63], v[182:185], 0
	v_mfma_f32_16x16x32_bf16 v[124:127], v[44:47], v[190:193], 0
	v_mfma_f32_16x16x32_bf16 v[120:123], v[60:63], v[190:193], 0
	v_mfma_f32_16x16x32_bf16 v[108:111], v[44:47], v[198:201], 0
	v_mfma_f32_16x16x32_bf16 v[104:107], v[60:63], v[198:201], 0
	v_mfma_f32_16x16x32_bf16 v[92:95], v[44:47], v[206:209], 0
	v_mfma_f32_16x16x32_bf16 v[88:91], v[60:63], v[206:209], 0
	v_mfma_f32_16x16x32_bf16 v[140:143], v[52:55], v[186:189], v[140:143]
	v_mfma_f32_16x16x32_bf16 v[136:139], v[68:71], v[186:189], v[136:139]
	v_mfma_f32_16x16x32_bf16 v[124:127], v[52:55], v[194:197], v[124:127]
	v_mfma_f32_16x16x32_bf16 v[120:123], v[68:71], v[194:197], v[120:123]
	v_mfma_f32_16x16x32_bf16 v[108:111], v[52:55], v[202:205], v[108:111]
	v_mfma_f32_16x16x32_bf16 v[104:107], v[68:71], v[202:205], v[104:107]
	v_mfma_f32_16x16x32_bf16 v[92:95], v[52:55], v[210:213], v[92:95]
	v_mfma_f32_16x16x32_bf16 v[88:91], v[68:71], v[210:213], v[88:91]
	s_setprio 0
	s_setprio 1
	v_mfma_f32_16x16x32_bf16 v[132:135], v[166:169], v[182:185], 0
	v_mfma_f32_16x16x32_bf16 v[128:131], v[174:177], v[182:185], 0
	v_mfma_f32_16x16x32_bf16 v[116:119], v[166:169], v[190:193], 0
	v_mfma_f32_16x16x32_bf16 v[112:115], v[174:177], v[190:193], 0
	v_mfma_f32_16x16x32_bf16 v[100:103], v[166:169], v[198:201], 0
	v_mfma_f32_16x16x32_bf16 v[96:99], v[174:177], v[198:201], 0
	v_mfma_f32_16x16x32_bf16 v[84:87], v[166:169], v[206:209], 0
	v_mfma_f32_16x16x32_bf16 v[80:83], v[174:177], v[206:209], 0
	v_mfma_f32_16x16x32_bf16 v[132:135], v[170:173], v[186:189], v[132:135]
	v_mfma_f32_16x16x32_bf16 v[128:131], v[178:181], v[186:189], v[128:131]
	v_mfma_f32_16x16x32_bf16 v[116:119], v[170:173], v[194:197], v[116:119]
	v_mfma_f32_16x16x32_bf16 v[112:115], v[178:181], v[194:197], v[112:115]
	v_mfma_f32_16x16x32_bf16 v[100:103], v[170:173], v[202:205], v[100:103]
	v_mfma_f32_16x16x32_bf16 v[96:99], v[178:181], v[202:205], v[96:99]
	v_mfma_f32_16x16x32_bf16 v[84:87], v[170:173], v[210:213], v[84:87]
	v_mfma_f32_16x16x32_bf16 v[80:83], v[178:181], v[210:213], v[80:83]
	s_setprio 0
	s_barrier
	s_add_i32 s9, s75, s55
	v_lshl_add_u64 v[158:159], s[76:77], 0, v[148:149]
	s_mov_b32 m0, s9
	ds_read_b128 v[182:185], v165 offset:16384
	ds_read_b128 v[186:189], v165 offset:17408
	ds_read_b128 v[190:193], v165 offset:18432
	ds_read_b128 v[194:197], v165 offset:19456
	ds_read_b128 v[198:201], v165 offset:20480
	ds_read_b128 v[202:205], v165 offset:21504
	ds_read_b128 v[206:209], v165 offset:22528
	ds_read_b128 v[210:213], v165 offset:23552
	global_load_lds_dwordx4 v[158:159], off
	s_add_i32 m0, s9, 0x2000
	v_lshl_add_u64 v[214:215], s[76:77], 0, v[144:145]
	s_add_u32 s76, s76, s12
	s_addc_u32 s77, s77, s13
	s_add_i32 s9, s78, s55
	global_load_lds_dwordx4 v[214:215], off
	v_lshl_add_u64 v[216:217], s[76:77], 0, v[148:149]
	s_mov_b32 m0, s9
	v_lshl_add_u64 v[218:219], s[76:77], 0, v[144:145]
	global_load_lds_dwordx4 v[216:217], off
	s_add_i32 m0, s9, 0x2000
	v_lshl_add_u64 v[220:221], s[6:7], 0, v[150:151]
	global_load_lds_dwordx4 v[218:219], off
	s_mov_b32 m0, s63
	v_lshl_add_u64 v[222:223], s[6:7], 0, v[146:147]
	global_load_lds_dwordx4 v[220:221], off
	s_mov_b32 m0, s64
	s_nop 0
	global_load_lds_dwordx4 v[222:223], off
	s_waitcnt vmcnt(8)
	s_waitcnt lgkmcnt(0)
	s_barrier
; #define PG8_STAGE(bufoff, gbase, voff) do { _Pragma("unroll") for (int _i = 0; _i < 2; ++_i) \
;         __builtin_amdgcn_global_load_lds((const unsigned*)((const char*)(gbase) + (voff)[_i]), (PG8_LAS unsigned*)(lds + (bufoff) + ldsw + _i * 8192), 16, 0, 0); } while (0)
; #define PG8_LDA(dst, b, h) do { _Pragma("unroll") for (int m = 0; m < 4; ++m) _Pragma("unroll") for (int k = 0; k < 2; ++k) dst[m][k] = *(const PG8_LAS bf16x8*)(lds + PG8_SA(b, h) + aoff + m * 2048 + k * 1024); } while (0)
; #define PG8_LDB(dst, b, h) do { _Pragma("unroll") for (int n = 0; n < 2; ++n) _Pragma("unroll") for (int k = 0; k < 2; ++k) dst[n][k] = *(const PG8_LAS bf16x8*)(lds + PG8_SB(b, h) + boff + n * 2048 + k * 1024); } while (0)
; #define PG8_MMA(ai, bj, At, Bt) do { __builtin_amdgcn_s_setprio(1); _Pragma("unroll") for (int m = 0; m < 4; ++m) _Pragma("unroll") for (int n = 0; n < 2; ++n) _Pragma("unroll") for (int k = 0; k < 2; ++k) \
;         acc[ai][bj][m][n] = __builtin_amdgcn_mfma_f32_16x16x32_bf16(Bt[n][k], At[m][k], acc[ai][bj][m][n], 0, 0, 0); __builtin_amdgcn_s_setprio(0); } while (0)
; #define PG8_WAIT_V(n) asm volatile("s_waitcnt vmcnt(" #n ")" ::: "memory")
; #define PG8_WAIT_L(n) asm volatile("s_waitcnt lgkmcnt(" #n ")" ::: "memory")
; #define PG8_BAR __builtin_amdgcn_s_barrier()
; #define PG8_SCHED __builtin_amdgcn_sched_barrier(0)
; template <class Epi, class Sched, bool ALIGN_EPI = false, bool SP2 = false>
; __device__ __forceinline__ void gemm_phase(PG8_LAS unsigned char* lds, const Gemm g, const Sched& S, const Epi& E, const int wid) {
;     ...
;             PG8_WAIT_V(8); PG8_WAIT_L(0); PG8_BAR; PG8_MMA(1, 0, At, B0); PG8_MMA(1, 1, At, B1); PG8_BAR; PG8_SCHED;
;             PG8_LDB(B0, 1, 0); PG8_LDB(B1, 1, 1); PG8_SCHED; PG8_LDA(At, 1, 0); PG8_STAGE(PG8_SA(0, 1), a2 + hstep, voffA);
;             PG8_WAIT_V(8); PG8_WAIT_L(0); PG8_BAR; PG8_MMA(0, 0, At, B0); PG8_MMA(0, 1, At, B1); PG8_BAR; PG8_SCHED;
	s_setprio 1
	s_waitcnt lgkmcnt(0)
	v_mfma_f32_16x16x32_bf16 v[76:79], v[44:47], v[182:185], 0
	v_mfma_f32_16x16x32_bf16 v[72:75], v[60:63], v[182:185], 0
	v_mfma_f32_16x16x32_bf16 v[48:51], v[44:47], v[190:193], 0
	v_mfma_f32_16x16x32_bf16 v[40:43], v[60:63], v[190:193], 0
	v_mfma_f32_16x16x32_bf16 v[28:31], v[44:47], v[198:201], 0
	v_mfma_f32_16x16x32_bf16 v[24:27], v[60:63], v[198:201], 0
	v_mfma_f32_16x16x32_bf16 v[12:15], v[44:47], v[206:209], 0
	v_mfma_f32_16x16x32_bf16 v[8:11], v[60:63], v[206:209], 0
	v_mfma_f32_16x16x32_bf16 v[76:79], v[52:55], v[186:189], v[76:79]
	v_mfma_f32_16x16x32_bf16 v[72:75], v[68:71], v[186:189], v[72:75]
	v_mfma_f32_16x16x32_bf16 v[48:51], v[52:55], v[194:197], v[48:51]
	v_mfma_f32_16x16x32_bf16 v[40:43], v[68:71], v[194:197], v[40:43]
	v_mfma_f32_16x16x32_bf16 v[28:31], v[52:55], v[202:205], v[28:31]
	v_mfma_f32_16x16x32_bf16 v[24:27], v[68:71], v[202:205], v[24:27]
	v_mfma_f32_16x16x32_bf16 v[12:15], v[52:55], v[210:213], v[12:15]
	v_mfma_f32_16x16x32_bf16 v[8:11], v[68:71], v[210:213], v[8:11]
	s_setprio 0
	s_setprio 1
	v_mfma_f32_16x16x32_bf16 v[36:39], v[166:169], v[190:193], 0
	v_mfma_f32_16x16x32_bf16 v[32:35], v[174:177], v[190:193], 0
	v_mfma_f32_16x16x32_bf16 v[20:23], v[166:169], v[198:201], 0
	v_mfma_f32_16x16x32_bf16 v[16:19], v[174:177], v[198:201], 0
	v_mfma_f32_16x16x32_bf16 v[4:7], v[166:169], v[206:209], 0
	v_mfma_f32_16x16x32_bf16 v[0:3], v[174:177], v[206:209], 0
	v_mfma_f32_16x16x32_bf16 v[44:47], v[166:169], v[182:185], 0
	v_mfma_f32_16x16x32_bf16 v[52:55], v[174:177], v[182:185], 0
	v_mfma_f32_16x16x32_bf16 v[36:39], v[170:173], v[194:197], v[36:39]
	v_mfma_f32_16x16x32_bf16 v[32:35], v[178:181], v[194:197], v[32:35]
	v_mfma_f32_16x16x32_bf16 v[20:23], v[170:173], v[202:205], v[20:23]
	v_mfma_f32_16x16x32_bf16 v[16:19], v[178:181], v[202:205], v[16:19]
	v_mfma_f32_16x16x32_bf16 v[4:7], v[170:173], v[210:213], v[4:7]
	v_mfma_f32_16x16x32_bf16 v[0:3], v[178:181], v[210:213], v[0:3]
	v_mfma_f32_16x16x32_bf16 v[44:47], v[170:173], v[186:189], v[44:47]
	v_mfma_f32_16x16x32_bf16 v[52:55], v[178:181], v[186:189], v[52:55]
	s_setprio 0
	s_barrier
	s_add_i32 s9, 0, 0x18000
	s_add_i32 s33, 0, 0x1c000
	v_add_u32_e32 v68, s9, v162
	v_add_u32_e32 v178, s33, v162
	ds_read_b128 v[56:59], v68
	ds_read_b128 v[60:63], v68 offset:1024
	ds_read_b128 v[64:67], v68 offset:2048
	ds_read_b128 v[68:71], v68 offset:3072
	ds_read_b128 v[166:169], v178
	ds_read_b128 v[170:173], v178 offset:1024
	ds_read_b128 v[174:177], v178 offset:2048
	ds_read_b128 v[178:181], v178 offset:3072
	s_add_u32 s6, s6, s12
	s_addc_u32 s7, s7, s13
	s_mov_b32 m0, s65
	v_lshl_add_u64 v[224:225], s[6:7], 0, v[150:151]
	ds_read_b128 v[182:185], v165 offset:32768
	ds_read_b128 v[186:189], v165 offset:33792
	ds_read_b128 v[190:193], v165 offset:34816
	ds_read_b128 v[194:197], v165 offset:35840
	ds_read_b128 v[198:201], v165 offset:36864
	ds_read_b128 v[202:205], v165 offset:37888
	ds_read_b128 v[206:209], v165 offset:38912
	ds_read_b128 v[210:213], v165 offset:39936
	global_load_lds_dwordx4 v[224:225], off
	v_lshl_add_u64 v[224:225], s[6:7], 0, v[146:147]
	s_mov_b32 m0, s66
	s_nop 0
	global_load_lds_dwordx4 v[224:225], off
	s_waitcnt vmcnt(8)
	s_waitcnt lgkmcnt(0)
	s_barrier
	s_setprio 1
	s_waitcnt lgkmcnt(0)
	v_mfma_f32_16x16x32_bf16 v[140:143], v[56:59], v[182:185], v[140:143]
	v_mfma_f32_16x16x32_bf16 v[136:139], v[64:67], v[182:185], v[136:139]
	v_mfma_f32_16x16x32_bf16 v[124:127], v[56:59], v[190:193], v[124:127]
	v_mfma_f32_16x16x32_bf16 v[120:123], v[64:67], v[190:193], v[120:123]
	v_mfma_f32_16x16x32_bf16 v[108:111], v[56:59], v[198:201], v[108:111]
	v_mfma_f32_16x16x32_bf16 v[104:107], v[64:67], v[198:201], v[104:107]
	v_mfma_f32_16x16x32_bf16 v[92:95], v[56:59], v[206:209], v[92:95]
	v_mfma_f32_16x16x32_bf16 v[88:91], v[64:67], v[206:209], v[88:91]
	v_mfma_f32_16x16x32_bf16 v[140:143], v[60:63], v[186:189], v[140:143]
	v_mfma_f32_16x16x32_bf16 v[136:139], v[68:71], v[186:189], v[136:139]
	v_mfma_f32_16x16x32_bf16 v[124:127], v[60:63], v[194:197], v[124:127]
	v_mfma_f32_16x16x32_bf16 v[120:123], v[68:71], v[194:197], v[120:123]
	v_mfma_f32_16x16x32_bf16 v[108:111], v[60:63], v[202:205], v[108:111]
	v_mfma_f32_16x16x32_bf16 v[104:107], v[68:71], v[202:205], v[104:107]
	v_mfma_f32_16x16x32_bf16 v[92:95], v[60:63], v[210:213], v[92:95]
	v_mfma_f32_16x16x32_bf16 v[88:91], v[68:71], v[210:213], v[88:91]
	s_setprio 0
	s_setprio 1
	v_mfma_f32_16x16x32_bf16 v[132:135], v[166:169], v[182:185], v[132:135]
	v_mfma_f32_16x16x32_bf16 v[128:131], v[174:177], v[182:185], v[128:131]
	v_mfma_f32_16x16x32_bf16 v[116:119], v[166:169], v[190:193], v[116:119]
	v_mfma_f32_16x16x32_bf16 v[112:115], v[174:177], v[190:193], v[112:115]
	v_mfma_f32_16x16x32_bf16 v[100:103], v[166:169], v[198:201], v[100:103]
	v_mfma_f32_16x16x32_bf16 v[96:99], v[174:177], v[198:201], v[96:99]
	v_mfma_f32_16x16x32_bf16 v[84:87], v[166:169], v[206:209], v[84:87]
	v_mfma_f32_16x16x32_bf16 v[80:83], v[174:177], v[206:209], v[80:83]
	v_mfma_f32_16x16x32_bf16 v[132:135], v[170:173], v[186:189], v[132:135]
	v_mfma_f32_16x16x32_bf16 v[128:131], v[178:181], v[186:189], v[128:131]
	v_mfma_f32_16x16x32_bf16 v[116:119], v[170:173], v[194:197], v[116:119]
	v_mfma_f32_16x16x32_bf16 v[112:115], v[178:181], v[194:197], v[112:115]
	v_mfma_f32_16x16x32_bf16 v[100:103], v[170:173], v[202:205], v[100:103]
	v_mfma_f32_16x16x32_bf16 v[96:99], v[178:181], v[202:205], v[96:99]
	v_mfma_f32_16x16x32_bf16 v[84:87], v[170:173], v[210:213], v[84:87]
	v_mfma_f32_16x16x32_bf16 v[80:83], v[178:181], v[210:213], v[80:83]
	s_setprio 0
	s_barrier
; #define PG8_STAGE(bufoff, gbase, voff) do { _Pragma("unroll") for (int _i = 0; _i < 2; ++_i) \
;         __builtin_amdgcn_global_load_lds((const unsigned*)((const char*)(gbase) + (voff)[_i]), (PG8_LAS unsigned*)(lds + (bufoff) + ldsw + _i * 8192), 16, 0, 0); } while (0)
; #define PG8_LDA(dst, b, h) do { _Pragma("unroll") for (int m = 0; m < 4; ++m) _Pragma("unroll") for (int k = 0; k < 2; ++k) dst[m][k] = *(const PG8_LAS bf16x8*)(lds + PG8_SA(b, h) + aoff + m * 2048 + k * 1024); } while (0)
; #define PG8_MMA(ai, bj, At, Bt) do { __builtin_amdgcn_s_setprio(1); _Pragma("unroll") for (int m = 0; m < 4; ++m) _Pragma("unroll") for (int n = 0; n < 2; ++n) _Pragma("unroll") for (int k = 0; k < 2; ++k) \
;         acc[ai][bj][m][n] = __builtin_amdgcn_mfma_f32_16x16x32_bf16(Bt[n][k], At[m][k], acc[ai][bj][m][n], 0, 0, 0); __builtin_amdgcn_s_setprio(0); } while (0)
; #define PG8_WAIT_V(n) asm volatile("s_waitcnt vmcnt(" #n ")" ::: "memory")
; #define PG8_WAIT_L(n) asm volatile("s_waitcnt lgkmcnt(" #n ")" ::: "memory")
; #define PG8_BAR __builtin_amdgcn_s_barrier()
; #define PG8_SCHED __builtin_amdgcn_sched_barrier(0)
; template <class Epi, class Sched, bool ALIGN_EPI = false, bool SP2 = false>
; __device__ __forceinline__ void gemm_phase(PG8_LAS unsigned char* lds, const Gemm g, const Sched& S, const Epi& E, const int wid) {
;     ...
;         for (int t = 0; t < nt; t += 2) {
;             const bool last = (t == nt - 2);
;             const char* a1 = cA + (size_t)(t + 1) * kstep;
;             const char* a2 = last ? nA : cA + (size_t)(t + 2) * kstep; const char* b2 = last ? nB : cB + (size_t)(t + 2) * kstep;
;     ...
;             PG8_LDA(At, 1, 1); PG8_STAGE(PG8_SB(1, 0), b3, voffB); PG8_STAGE(PG8_SB(1, 1), b3 + hstep, voffB); PG8_STAGE(PG8_SA(1, 0), a3, voffA);
;             PG8_WAIT_V(8); PG8_WAIT_L(0); PG8_BAR; PG8_MMA(1, 0, At, B0); PG8_MMA(1, 1, At, B1); PG8_BAR; PG8_SCHED;
	s_add_i32 s6, s9, s55
	v_lshl_add_u64 v[158:159], v[158:159], 0, s[26:27]
	s_mov_b32 m0, s6
	ds_read_b128 v[182:185], v165 offset:49152
	ds_read_b128 v[186:189], v165 offset:50176
	ds_read_b128 v[190:193], v165 offset:51200
	ds_read_b128 v[194:197], v165 offset:52224
	ds_read_b128 v[198:201], v165 offset:53248
	ds_read_b128 v[202:205], v165 offset:54272
	ds_read_b128 v[206:209], v165 offset:55296
	ds_read_b128 v[210:213], v165 offset:56320
	global_load_lds_dwordx4 v[158:159], off
	v_lshl_add_u64 v[158:159], v[214:215], 0, s[26:27]
	s_add_i32 m0, s6, 0x2000
	s_add_i32 s6, s33, s55
	global_load_lds_dwordx4 v[158:159], off
	v_lshl_add_u64 v[158:159], v[216:217], 0, s[26:27]
	s_mov_b32 m0, s6
	s_nop 0
	global_load_lds_dwordx4 v[158:159], off
	v_lshl_add_u64 v[158:159], v[218:219], 0, s[26:27]
	s_add_i32 m0, s6, 0x2000
	s_nop 0
	global_load_lds_dwordx4 v[158:159], off
	v_lshl_add_u64 v[158:159], v[220:221], 0, s[26:27]
	s_mov_b32 m0, s68
	s_nop 0
	global_load_lds_dwordx4 v[158:159], off
	v_lshl_add_u64 v[158:159], v[222:223], 0, s[26:27]
	s_mov_b32 m0, s69
	s_nop 0
	global_load_lds_dwordx4 v[158:159], off
	s_waitcnt vmcnt(8)
	s_waitcnt lgkmcnt(0)
	s_barrier
	s_setprio 1
	s_waitcnt lgkmcnt(0)
	v_mfma_f32_16x16x32_bf16 v[76:79], v[56:59], v[182:185], v[76:79]
	v_mfma_f32_16x16x32_bf16 v[72:75], v[64:67], v[182:185], v[72:75]
	v_mfma_f32_16x16x32_bf16 v[48:51], v[56:59], v[190:193], v[48:51]
	v_mfma_f32_16x16x32_bf16 v[40:43], v[64:67], v[190:193], v[40:43]
	v_mfma_f32_16x16x32_bf16 v[28:31], v[56:59], v[198:201], v[28:31]
	v_mfma_f32_16x16x32_bf16 v[24:27], v[64:67], v[198:201], v[24:27]
	v_mfma_f32_16x16x32_bf16 v[12:15], v[56:59], v[206:209], v[12:15]
	v_mfma_f32_16x16x32_bf16 v[8:11], v[64:67], v[206:209], v[8:11]
	v_mfma_f32_16x16x32_bf16 v[76:79], v[60:63], v[186:189], v[76:79]
	v_mfma_f32_16x16x32_bf16 v[72:75], v[68:71], v[186:189], v[72:75]
	v_mfma_f32_16x16x32_bf16 v[48:51], v[60:63], v[194:197], v[48:51]
	v_mfma_f32_16x16x32_bf16 v[40:43], v[68:71], v[194:197], v[40:43]
	v_mfma_f32_16x16x32_bf16 v[28:31], v[60:63], v[202:205], v[28:31]
	v_mfma_f32_16x16x32_bf16 v[24:27], v[68:71], v[202:205], v[24:27]
	v_mfma_f32_16x16x32_bf16 v[12:15], v[60:63], v[210:213], v[12:15]
	v_mfma_f32_16x16x32_bf16 v[8:11], v[68:71], v[210:213], v[8:11]
	s_setprio 0
	s_setprio 1
	v_mfma_f32_16x16x32_bf16 v[44:47], v[166:169], v[182:185], v[44:47]
	v_mfma_f32_16x16x32_bf16 v[64:67], v[170:173], v[186:189], v[44:47]
	v_mfma_f32_16x16x32_bf16 v[44:47], v[174:177], v[182:185], v[52:55]
	v_mfma_f32_16x16x32_bf16 v[36:39], v[166:169], v[190:193], v[36:39]
	v_mfma_f32_16x16x32_bf16 v[32:35], v[174:177], v[190:193], v[32:35]
	v_mfma_f32_16x16x32_bf16 v[20:23], v[166:169], v[198:201], v[20:23]
	v_mfma_f32_16x16x32_bf16 v[16:19], v[174:177], v[198:201], v[16:19]
	v_mfma_f32_16x16x32_bf16 v[4:7], v[166:169], v[206:209], v[4:7]
	v_mfma_f32_16x16x32_bf16 v[0:3], v[174:177], v[206:209], v[0:3]
	v_mfma_f32_16x16x32_bf16 v[56:59], v[178:181], v[186:189], v[44:47]
	v_mfma_f32_16x16x32_bf16 v[36:39], v[170:173], v[194:197], v[36:39]
	v_mfma_f32_16x16x32_bf16 v[32:35], v[178:181], v[194:197], v[32:35]
	v_mfma_f32_16x16x32_bf16 v[20:23], v[170:173], v[202:205], v[20:23]
	v_mfma_f32_16x16x32_bf16 v[16:19], v[178:181], v[202:205], v[16:19]
	v_mfma_f32_16x16x32_bf16 v[4:7], v[170:173], v[210:213], v[4:7]
	v_mfma_f32_16x16x32_bf16 v[0:3], v[178:181], v[210:213], v[0:3]
	s_setprio 0
	s_barrier
	s_add_u32 s4, s4, 0x100
	s_addc_u32 s5, s5, 0
	s_add_u32 s0, s0, 0x100
	s_addc_u32 s1, s1, 0
	s_cmp_ge_i32 s8, s70
	s_mov_b32 s6, s8
	s_cbranch_scc1 .LBB0_1101

; template <class Epi, class Sched, bool ALIGN_EPI = false, bool SP2 = false>
; __device__ __forceinline__ void gemm_phase(PG8_LAS unsigned char* lds, const Gemm g, const Sched& S, const Epi& E, const int wid) {
;     ...
;         for (int a = 0; a < 2; ++a)
; #pragma unroll
;             for (int b = 0; b < 2; ++b)
; #pragma unroll
;                 for (int m = 0; m < 4; ++m)
; #pragma unroll
;                     for (int n = 0; n < 2; ++n) acc[a][b][m][n] = (f32x4){0.f, 0.f, 0.f, 0.f};
.Lz_G1B:
	v_mov_b32_e32 v143, 0
	v_mov_b32_e32 v142, v143
	v_mov_b32_e32 v141, v143
	v_mov_b32_e32 v140, v143
	v_mov_b32_e32 v139, v143
	v_mov_b32_e32 v138, v143
	v_mov_b32_e32 v137, v143
	v_mov_b32_e32 v136, v143
	v_mov_b32_e32 v127, v143
	v_mov_b32_e32 v126, v143
	v_mov_b32_e32 v125, v143
	v_mov_b32_e32 v124, v143
	v_mov_b32_e32 v123, v143
	v_mov_b32_e32 v122, v143
	v_mov_b32_e32 v121, v143
	v_mov_b32_e32 v120, v143
	v_mov_b32_e32 v111, v143
	v_mov_b32_e32 v110, v143
	v_mov_b32_e32 v109, v143
	v_mov_b32_e32 v108, v143
	v_mov_b32_e32 v107, v143
	v_mov_b32_e32 v106, v143
	v_mov_b32_e32 v105, v143
	v_mov_b32_e32 v104, v143
	v_mov_b32_e32 v95, v143
	v_mov_b32_e32 v94, v143
	v_mov_b32_e32 v93, v143
	v_mov_b32_e32 v92, v143
	v_mov_b32_e32 v91, v143
	v_mov_b32_e32 v90, v143
	v_mov_b32_e32 v89, v143
	v_mov_b32_e32 v88, v143
	v_mov_b32_e32 v135, v143
	v_mov_b32_e32 v134, v143
	v_mov_b32_e32 v133, v143
	v_mov_b32_e32 v132, v143
	v_mov_b32_e32 v131, v143
	v_mov_b32_e32 v130, v143
	v_mov_b32_e32 v129, v143
	v_mov_b32_e32 v128, v143
	v_mov_b32_e32 v119, v143
	v_mov_b32_e32 v118, v143
	v_mov_b32_e32 v117, v143
	v_mov_b32_e32 v116, v143
	v_mov_b32_e32 v115, v143
	v_mov_b32_e32 v114, v143
	v_mov_b32_e32 v113, v143
	v_mov_b32_e32 v112, v143
	v_mov_b32_e32 v103, v143
	v_mov_b32_e32 v102, v143
	v_mov_b32_e32 v101, v143
	v_mov_b32_e32 v100, v143
	v_mov_b32_e32 v99, v143
	v_mov_b32_e32 v98, v143
	v_mov_b32_e32 v97, v143
	v_mov_b32_e32 v96, v143
	v_mov_b32_e32 v87, v143
	v_mov_b32_e32 v86, v143
	v_mov_b32_e32 v85, v143
	v_mov_b32_e32 v84, v143
	v_mov_b32_e32 v83, v143
	v_mov_b32_e32 v82, v143
	v_mov_b32_e32 v81, v143
	v_mov_b32_e32 v80, v143
	v_mov_b32_e32 v79, v143
	v_mov_b32_e32 v78, v143
	v_mov_b32_e32 v77, v143
	v_mov_b32_e32 v76, v143
	v_mov_b32_e32 v75, v143
	v_mov_b32_e32 v74, v143
	v_mov_b32_e32 v73, v143
	v_mov_b32_e32 v72, v143
	v_mov_b32_e32 v51, v143
	v_mov_b32_e32 v50, v143
	v_mov_b32_e32 v49, v143
	v_mov_b32_e32 v48, v143
	v_mov_b32_e32 v43, v143
	v_mov_b32_e32 v42, v143
	v_mov_b32_e32 v41, v143
	v_mov_b32_e32 v40, v143
	v_mov_b32_e32 v31, v143
	v_mov_b32_e32 v30, v143
	v_mov_b32_e32 v29, v143
	v_mov_b32_e32 v28, v143
	v_mov_b32_e32 v27, v143
	v_mov_b32_e32 v26, v143
	v_mov_b32_e32 v25, v143
	v_mov_b32_e32 v24, v143
	v_mov_b32_e32 v15, v143
	v_mov_b32_e32 v14, v143
	v_mov_b32_e32 v13, v143
	v_mov_b32_e32 v12, v143
	v_mov_b32_e32 v11, v143
	v_mov_b32_e32 v10, v143
	v_mov_b32_e32 v9, v143
	v_mov_b32_e32 v8, v143
	v_mov_b32_e32 v67, v143
	v_mov_b32_e32 v66, v143
	v_mov_b32_e32 v65, v143
	v_mov_b32_e32 v64, v143
	v_mov_b32_e32 v59, v143
	v_mov_b32_e32 v58, v143
	v_mov_b32_e32 v57, v143
	v_mov_b32_e32 v56, v143
	v_mov_b32_e32 v39, v143
	v_mov_b32_e32 v38, v143
	v_mov_b32_e32 v37, v143
	v_mov_b32_e32 v36, v143
	v_mov_b32_e32 v35, v143
	v_mov_b32_e32 v34, v143
	v_mov_b32_e32 v33, v143
	v_mov_b32_e32 v32, v143
	v_mov_b32_e32 v23, v143
	v_mov_b32_e32 v22, v143
	v_mov_b32_e32 v21, v143
	v_mov_b32_e32 v20, v143
	v_mov_b32_e32 v19, v143
	v_mov_b32_e32 v18, v143
	v_mov_b32_e32 v17, v143
	v_mov_b32_e32 v16, v143
	v_mov_b32_e32 v7, v143
	v_mov_b32_e32 v6, v143
	v_mov_b32_e32 v5, v143
	v_mov_b32_e32 v4, v143
	v_mov_b32_e32 v3, v143
	v_mov_b32_e32 v2, v143
	v_mov_b32_e32 v1, v143
	v_mov_b32_e32 v0, v143
	s_branch .LBB0_1101
